# v55 + first K-iteration of z/MLP1 tiles after the first waits vmcnt(24) instead of vmcnt(8): the 16 epilogue stores stay in flight
# baseline (speedup 1.0000x reference)
; #define PG8_STAGE(bufoff, gbase, voff) do { _Pragma("unroll") for (int _i = 0; _i < 2; ++_i) \
;         __builtin_amdgcn_global_load_lds((const unsigned*)((const char*)(gbase) + (voff)[_i]), (LAS unsigned*)(lds + (bufoff) + ldsw + _i * 8192), 16, 0, 0); } while (0)
; #define PG8_LDA(dst, b, h) do { _Pragma("unroll") for (int m = 0; m < 4; ++m) _Pragma("unroll") for (int k = 0; k < 2; ++k) dst[m][k] = *(const LAS bf16x8*)(lds + PG8_SA(b, h) + aoff + m * 2048 + k * 1024); } while (0)
; #define PG8_LDB(dst, b, h) do { _Pragma("unroll") for (int n = 0; n < 2; ++n) _Pragma("unroll") for (int k = 0; k < 2; ++k) dst[n][k] = *(const LAS bf16x8*)(lds + PG8_SB(b, h) + boff + n * 2048 + k * 1024); } while (0)
; #define PG8_MMA(ai, bj, At, Bt) do { __builtin_amdgcn_s_setprio(1); _Pragma("unroll") for (int m = 0; m < 4; ++m) _Pragma("unroll") for (int n = 0; n < 2; ++n) _Pragma("unroll") for (int k = 0; k < 2; ++k) \
;         acc[ai][bj][m][n] = __builtin_amdgcn_mfma_f32_16x16x32_bf16(Bt[n][k], At[m][k], acc[ai][bj][m][n], 0, 0, 0); __builtin_amdgcn_s_setprio(0); } while (0)
; #define PG8_WAIT_V(n) asm volatile("s_waitcnt vmcnt(" #n ")" ::: "memory")
; #define PG8_WAIT_L(n) asm volatile("s_waitcnt lgkmcnt(" #n ")" ::: "memory")
; #define PG8_BAR __builtin_amdgcn_s_barrier()
; template <class Epi, class Sched>
; __device__ __forceinline__ void gemm_phase(LAS unsigned char* lds, const Gemm g, const Sched& S, const Epi& E) {
;     ...
;         for (int t = 0; t < nt; t += 2) {
;             const bool last = (t == nt - 2);
;             const char* a1 = cA + (size_t)(t + 1) * kstep;
;             const char* a2 = last ? nA : cA + (size_t)(t + 2) * kstep; const char* b2 = last ? nB : cB + (size_t)(t + 2) * kstep;
;             const char* a3 = a2 + kstep; const char* b3 = b2 + kstep;
;             if (last && has_next) S.a_ready(nxt);
;             PG8_LDB(B0, 0, 0); PG8_LDB(B1, 0, 1); PG8_SCHED; PG8_LDA(At, 0, 0); PG8_STAGE(PG8_SA(1, 1), a1 + hstep, voffA);
;             PG8_WAIT_V(8); PG8_WAIT_L(0); PG8_BAR; PG8_MMA(0, 0, At, B0); PG8_MMA(0, 1, At, B1); PG8_BAR; PG8_SCHED;
;             PG8_LDA(At, 0, 1); PG8_STAGE(PG8_SB(0, 0), b2, voffB); PG8_STAGE(PG8_SB(0, 1), b2 + hstep, voffB); PG8_STAGE(PG8_SA(0, 0), a2, voffA);
;             PG8_WAIT_V(8); PG8_WAIT_L(0); PG8_BAR; PG8_MMA(1, 0, At, B0); PG8_MMA(1, 1, At, B1); PG8_BAR; PG8_SCHED;
.LBB0_131:
	s_cmp_eq_u32 s50, 0
	s_cselect_b32 s99, 1, 0
	s_cmp_eq_u32 s8, 0
	s_cselect_b32 s99, 0, s99
	s_add_i32 s58, s50, 2
	s_add_u32 s48, s46, 0x100
	s_addc_u32 s49, s47, 0
	s_add_u32 s1, s9, s46
	s_addc_u32 s51, s36, s47
	s_cmp_eq_u32 s56, s50
	s_cselect_b32 s50, 0, s48
	s_cselect_b32 s59, 0, s49
	s_cselect_b32 s60, s44, s1
	s_cselect_b32 s61, s45, s51
	s_add_u32 s50, s2, s50
	s_addc_u32 s51, s3, s59
	s_add_i32 s1, 0, 0x10000
	s_add_i32 s59, 0, 0x14000
	v_add_u32_e32 v156, s1, v142
	v_add_u32_e32 v172, s59, v142
	ds_read_b128 v[144:147], v156
	ds_read_b128 v[148:151], v156 offset:1024
	ds_read_b128 v[152:155], v156 offset:2048
	ds_read_b128 v[156:159], v156 offset:3072
	ds_read_b128 v[160:163], v172
	ds_read_b128 v[164:167], v172 offset:1024
	ds_read_b128 v[168:171], v172 offset:2048
	ds_read_b128 v[172:175], v172 offset:3072
	s_add_u32 s46, s46, s2
	s_addc_u32 s47, s47, s3
	s_add_u32 s46, s46, s20
	s_addc_u32 s47, s47, s21
	s_add_u32 s46, s46, 0x80
	s_addc_u32 s47, s47, 0
	s_add_i32 m0, s5, 0xc000
	ds_read_b128 v[176:179], v143
	ds_read_b128 v[180:183], v143 offset:1024
	ds_read_b128 v[184:187], v143 offset:2048
	ds_read_b128 v[192:195], v143 offset:3072
	ds_read_b128 v[196:199], v143 offset:4096
	ds_read_b128 v[200:203], v143 offset:5120
	ds_read_b128 v[204:207], v143 offset:6144
	ds_read_b128 v[208:211], v143 offset:7168
	global_load_lds_dwordx4 v134, s[46:47]
	s_add_i32 m0, s5, 0xe000
	s_nop 0
	global_load_lds_dwordx4 v132, s[46:47]
	s_cmp_eq_u32 s99, 1
	s_cbranch_scc1 .Lfw_z_0_first
	s_waitcnt vmcnt(8)
	s_branch .Lfw_z_0_join
.Lfw_z_0_first:
	s_waitcnt vmcnt(24)
.Lfw_z_0_join:
	s_waitcnt lgkmcnt(0)
	s_barrier
	s_setprio 1
	s_waitcnt lgkmcnt(0)
	v_mfma_f32_16x16x32_bf16 v[122:125], v[144:147], v[176:179], v[122:125]
	v_mfma_f32_16x16x32_bf16 v[126:129], v[152:155], v[176:179], v[126:129]
	v_mfma_f32_16x16x32_bf16 v[110:113], v[144:147], v[184:187], v[110:113]
	v_mfma_f32_16x16x32_bf16 v[106:109], v[152:155], v[184:187], v[106:109]
	v_mfma_f32_16x16x32_bf16 v[94:97], v[144:147], v[196:199], v[94:97]
	v_mfma_f32_16x16x32_bf16 v[90:93], v[152:155], v[196:199], v[90:93]
	v_mfma_f32_16x16x32_bf16 v[78:81], v[144:147], v[204:207], v[78:81]
	v_mfma_f32_16x16x32_bf16 v[74:77], v[152:155], v[204:207], v[74:77]
	v_mfma_f32_16x16x32_bf16 v[122:125], v[148:151], v[180:183], v[122:125]
	v_mfma_f32_16x16x32_bf16 v[126:129], v[156:159], v[180:183], v[126:129]
	v_mfma_f32_16x16x32_bf16 v[110:113], v[148:151], v[192:195], v[110:113]
	v_mfma_f32_16x16x32_bf16 v[106:109], v[156:159], v[192:195], v[106:109]
	v_mfma_f32_16x16x32_bf16 v[94:97], v[148:151], v[200:203], v[94:97]
	v_mfma_f32_16x16x32_bf16 v[90:93], v[156:159], v[200:203], v[90:93]
	v_mfma_f32_16x16x32_bf16 v[78:81], v[148:151], v[208:211], v[78:81]
	v_mfma_f32_16x16x32_bf16 v[74:77], v[156:159], v[208:211], v[74:77]
	s_setprio 0
	s_setprio 1
	v_mfma_f32_16x16x32_bf16 v[118:121], v[160:163], v[176:179], v[118:121]
	v_mfma_f32_16x16x32_bf16 v[114:117], v[168:171], v[176:179], v[114:117]
	v_mfma_f32_16x16x32_bf16 v[102:105], v[160:163], v[184:187], v[102:105]
	v_mfma_f32_16x16x32_bf16 v[98:101], v[168:171], v[184:187], v[98:101]
	v_mfma_f32_16x16x32_bf16 v[86:89], v[160:163], v[196:199], v[86:89]
	v_mfma_f32_16x16x32_bf16 v[82:85], v[168:171], v[196:199], v[82:85]
	v_mfma_f32_16x16x32_bf16 v[70:73], v[160:163], v[204:207], v[70:73]
	v_mfma_f32_16x16x32_bf16 v[66:69], v[168:171], v[204:207], v[66:69]
	v_mfma_f32_16x16x32_bf16 v[118:121], v[164:167], v[180:183], v[118:121]
	v_mfma_f32_16x16x32_bf16 v[114:117], v[172:175], v[180:183], v[114:117]
	v_mfma_f32_16x16x32_bf16 v[102:105], v[164:167], v[192:195], v[102:105]
	v_mfma_f32_16x16x32_bf16 v[98:101], v[172:175], v[192:195], v[98:101]
	v_mfma_f32_16x16x32_bf16 v[86:89], v[164:167], v[200:203], v[86:89]
	v_mfma_f32_16x16x32_bf16 v[82:85], v[172:175], v[200:203], v[82:85]
	v_mfma_f32_16x16x32_bf16 v[70:73], v[164:167], v[208:211], v[70:73]
	v_mfma_f32_16x16x32_bf16 v[66:69], v[172:175], v[208:211], v[66:69]
	s_setprio 0
	s_barrier
	s_add_i32 s1, s1, s4
	s_mov_b32 m0, s1
	ds_read_b128 v[176:179], v143 offset:16384
	ds_read_b128 v[180:183], v143 offset:17408
	ds_read_b128 v[184:187], v143 offset:18432
	ds_read_b128 v[192:195], v143 offset:19456
	ds_read_b128 v[196:199], v143 offset:20480
	ds_read_b128 v[200:203], v143 offset:21504
	ds_read_b128 v[204:207], v143 offset:22528
	ds_read_b128 v[208:211], v143 offset:23552
	global_load_lds_dwordx4 v0, s[60:61]
	s_add_i32 m0, s1, 0x2000
	s_add_u32 s46, s60, s20
	s_addc_u32 s47, s61, s21
	s_add_i32 s1, s59, s4
	global_load_lds_dwordx4 v130, s[60:61]
	s_mov_b32 m0, s1
	s_nop 0
	global_load_lds_dwordx4 v0, s[46:47]
	s_add_i32 m0, s1, 0x2000
	s_nop 0
	global_load_lds_dwordx4 v130, s[46:47]
	s_mov_b32 m0, s5
	s_nop 0
	global_load_lds_dwordx4 v134, s[50:51]
	s_mov_b32 m0, s18
	s_nop 0
	global_load_lds_dwordx4 v132, s[50:51]
	s_cmp_eq_u32 s99, 1
	s_cbranch_scc1 .Lfw_z_1_first
	s_waitcnt vmcnt(8)
	s_branch .Lfw_z_1_join

; #define PG8_STAGE(bufoff, gbase, voff) do { _Pragma("unroll") for (int _i = 0; _i < 2; ++_i) \
;         __builtin_amdgcn_global_load_lds((const unsigned*)((const char*)(gbase) + (voff)[_i]), (LAS unsigned*)(lds + (bufoff) + ldsw + _i * 8192), 16, 0, 0); } while (0)
; #define PG8_LDA(dst, b, h) do { _Pragma("unroll") for (int m = 0; m < 4; ++m) _Pragma("unroll") for (int k = 0; k < 2; ++k) dst[m][k] = *(const LAS bf16x8*)(lds + PG8_SA(b, h) + aoff + m * 2048 + k * 1024); } while (0)
; #define PG8_LDB(dst, b, h) do { _Pragma("unroll") for (int n = 0; n < 2; ++n) _Pragma("unroll") for (int k = 0; k < 2; ++k) dst[n][k] = *(const LAS bf16x8*)(lds + PG8_SB(b, h) + boff + n * 2048 + k * 1024); } while (0)
; #define PG8_MMA(ai, bj, At, Bt) do { __builtin_amdgcn_s_setprio(1); _Pragma("unroll") for (int m = 0; m < 4; ++m) _Pragma("unroll") for (int n = 0; n < 2; ++n) _Pragma("unroll") for (int k = 0; k < 2; ++k) \
;         acc[ai][bj][m][n] = __builtin_amdgcn_mfma_f32_16x16x32_bf16(Bt[n][k], At[m][k], acc[ai][bj][m][n], 0, 0, 0); __builtin_amdgcn_s_setprio(0); } while (0)
; #define PG8_WAIT_V(n) asm volatile("s_waitcnt vmcnt(" #n ")" ::: "memory")
; #define PG8_WAIT_L(n) asm volatile("s_waitcnt lgkmcnt(" #n ")" ::: "memory")
; #define PG8_BAR __builtin_amdgcn_s_barrier()
; #define PG8_SCHED __builtin_amdgcn_sched_barrier(0)
; template <class Epi, class Sched>
; __device__ __forceinline__ void gemm_phase(LAS unsigned char* lds, const Gemm g, const Sched& S, const Epi& E) {
;     ...
;             PG8_WAIT_V(8); PG8_WAIT_L(0); PG8_BAR; PG8_MMA(1, 0, At, B0); PG8_MMA(1, 1, At, B1); PG8_BAR; PG8_SCHED;
;             PG8_LDB(B0, 1, 0); PG8_LDB(B1, 1, 1); PG8_SCHED; PG8_LDA(At, 1, 0); PG8_STAGE(PG8_SA(0, 1), a2 + hstep, voffA);
;             PG8_WAIT_V(8); PG8_WAIT_L(0); PG8_BAR; PG8_MMA(0, 0, At, B0); PG8_MMA(0, 1, At, B1); PG8_BAR; PG8_SCHED;
;             PG8_LDA(At, 1, 1); PG8_STAGE(PG8_SB(1, 0), b3, voffB); PG8_STAGE(PG8_SB(1, 1), b3 + hstep, voffB); PG8_STAGE(PG8_SA(1, 0), a3, voffA);
.Lfw_z_1_join:
	s_waitcnt lgkmcnt(0)
	s_barrier
	s_setprio 1
	s_waitcnt lgkmcnt(0)
	v_mfma_f32_16x16x32_bf16 v[62:65], v[144:147], v[176:179], v[62:65]
	v_mfma_f32_16x16x32_bf16 v[58:61], v[152:155], v[176:179], v[58:61]
	v_mfma_f32_16x16x32_bf16 v[46:49], v[144:147], v[184:187], v[46:49]
	v_mfma_f32_16x16x32_bf16 v[42:45], v[152:155], v[184:187], v[42:45]
	v_mfma_f32_16x16x32_bf16 v[30:33], v[144:147], v[196:199], v[30:33]
	v_mfma_f32_16x16x32_bf16 v[26:29], v[152:155], v[196:199], v[26:29]
	v_mfma_f32_16x16x32_bf16 v[14:17], v[144:147], v[204:207], v[14:17]
	v_mfma_f32_16x16x32_bf16 v[10:13], v[152:155], v[204:207], v[10:13]
	v_mfma_f32_16x16x32_bf16 v[62:65], v[148:151], v[180:183], v[62:65]
	v_mfma_f32_16x16x32_bf16 v[58:61], v[156:159], v[180:183], v[58:61]
	v_mfma_f32_16x16x32_bf16 v[46:49], v[148:151], v[192:195], v[46:49]
	v_mfma_f32_16x16x32_bf16 v[42:45], v[156:159], v[192:195], v[42:45]
	v_mfma_f32_16x16x32_bf16 v[30:33], v[148:151], v[200:203], v[30:33]
	v_mfma_f32_16x16x32_bf16 v[26:29], v[156:159], v[200:203], v[26:29]
	v_mfma_f32_16x16x32_bf16 v[14:17], v[148:151], v[208:211], v[14:17]
	v_mfma_f32_16x16x32_bf16 v[10:13], v[156:159], v[208:211], v[10:13]
	s_setprio 0
	s_setprio 1
	v_mfma_f32_16x16x32_bf16 v[54:57], v[160:163], v[176:179], v[54:57]
	v_mfma_f32_16x16x32_bf16 v[50:53], v[168:171], v[176:179], v[50:53]
	v_mfma_f32_16x16x32_bf16 v[38:41], v[160:163], v[184:187], v[38:41]
	v_mfma_f32_16x16x32_bf16 v[34:37], v[168:171], v[184:187], v[34:37]
	v_mfma_f32_16x16x32_bf16 v[22:25], v[160:163], v[196:199], v[22:25]
	v_mfma_f32_16x16x32_bf16 v[18:21], v[168:171], v[196:199], v[18:21]
	v_mfma_f32_16x16x32_bf16 v[6:9], v[160:163], v[204:207], v[6:9]
	v_mfma_f32_16x16x32_bf16 v[2:5], v[168:171], v[204:207], v[2:5]
	v_mfma_f32_16x16x32_bf16 v[54:57], v[164:167], v[180:183], v[54:57]
	v_mfma_f32_16x16x32_bf16 v[50:53], v[172:175], v[180:183], v[50:53]
	v_mfma_f32_16x16x32_bf16 v[38:41], v[164:167], v[192:195], v[38:41]
	v_mfma_f32_16x16x32_bf16 v[34:37], v[172:175], v[192:195], v[34:37]
	v_mfma_f32_16x16x32_bf16 v[22:25], v[164:167], v[200:203], v[22:25]
	v_mfma_f32_16x16x32_bf16 v[18:21], v[172:175], v[200:203], v[18:21]
	v_mfma_f32_16x16x32_bf16 v[6:9], v[164:167], v[208:211], v[6:9]
	v_mfma_f32_16x16x32_bf16 v[2:5], v[172:175], v[208:211], v[2:5]
	s_setprio 0
	s_barrier
	s_add_i32 s1, 0, 0x18000
	s_add_i32 s59, 0, 0x1c000
	v_add_u32_e32 v156, s1, v142
	v_add_u32_e32 v172, s59, v142
	ds_read_b128 v[144:147], v156
	ds_read_b128 v[148:151], v156 offset:1024
	ds_read_b128 v[152:155], v156 offset:2048
	ds_read_b128 v[156:159], v156 offset:3072
	ds_read_b128 v[160:163], v172
	ds_read_b128 v[164:167], v172 offset:1024
	ds_read_b128 v[168:171], v172 offset:2048
	ds_read_b128 v[172:175], v172 offset:3072
	s_add_u32 s46, s50, s20
	s_addc_u32 s47, s51, s21
	s_mov_b32 m0, s19
	ds_read_b128 v[176:179], v143 offset:32768
	ds_read_b128 v[180:183], v143 offset:33792
	ds_read_b128 v[184:187], v143 offset:34816
	ds_read_b128 v[192:195], v143 offset:35840
	ds_read_b128 v[196:199], v143 offset:36864
	ds_read_b128 v[200:203], v143 offset:37888
	ds_read_b128 v[204:207], v143 offset:38912
	ds_read_b128 v[208:211], v143 offset:39936
	global_load_lds_dwordx4 v134, s[46:47]
	s_mov_b32 m0, s52
	s_nop 0
	global_load_lds_dwordx4 v132, s[46:47]
	s_waitcnt vmcnt(8)
	s_waitcnt lgkmcnt(0)
	s_barrier
	s_setprio 1
	s_waitcnt lgkmcnt(0)
	v_mfma_f32_16x16x32_bf16 v[122:125], v[144:147], v[176:179], v[122:125]
	v_mfma_f32_16x16x32_bf16 v[126:129], v[152:155], v[176:179], v[126:129]
	v_mfma_f32_16x16x32_bf16 v[110:113], v[144:147], v[184:187], v[110:113]
	v_mfma_f32_16x16x32_bf16 v[106:109], v[152:155], v[184:187], v[106:109]
	v_mfma_f32_16x16x32_bf16 v[94:97], v[144:147], v[196:199], v[94:97]
	v_mfma_f32_16x16x32_bf16 v[90:93], v[152:155], v[196:199], v[90:93]
	v_mfma_f32_16x16x32_bf16 v[78:81], v[144:147], v[204:207], v[78:81]
	v_mfma_f32_16x16x32_bf16 v[74:77], v[152:155], v[204:207], v[74:77]
	v_mfma_f32_16x16x32_bf16 v[122:125], v[148:151], v[180:183], v[122:125]
	v_mfma_f32_16x16x32_bf16 v[126:129], v[156:159], v[180:183], v[126:129]
	v_mfma_f32_16x16x32_bf16 v[110:113], v[148:151], v[192:195], v[110:113]
	v_mfma_f32_16x16x32_bf16 v[106:109], v[156:159], v[192:195], v[106:109]
	v_mfma_f32_16x16x32_bf16 v[94:97], v[148:151], v[200:203], v[94:97]
	v_mfma_f32_16x16x32_bf16 v[90:93], v[156:159], v[200:203], v[90:93]
	v_mfma_f32_16x16x32_bf16 v[78:81], v[148:151], v[208:211], v[78:81]
	v_mfma_f32_16x16x32_bf16 v[74:77], v[156:159], v[208:211], v[74:77]
	s_setprio 0
	s_setprio 1
	v_mfma_f32_16x16x32_bf16 v[118:121], v[160:163], v[176:179], v[118:121]
	v_mfma_f32_16x16x32_bf16 v[114:117], v[168:171], v[176:179], v[114:117]
	v_mfma_f32_16x16x32_bf16 v[102:105], v[160:163], v[184:187], v[102:105]
	v_mfma_f32_16x16x32_bf16 v[98:101], v[168:171], v[184:187], v[98:101]
	v_mfma_f32_16x16x32_bf16 v[86:89], v[160:163], v[196:199], v[86:89]
	v_mfma_f32_16x16x32_bf16 v[82:85], v[168:171], v[196:199], v[82:85]
	v_mfma_f32_16x16x32_bf16 v[70:73], v[160:163], v[204:207], v[70:73]
	v_mfma_f32_16x16x32_bf16 v[66:69], v[168:171], v[204:207], v[66:69]
	v_mfma_f32_16x16x32_bf16 v[118:121], v[164:167], v[180:183], v[118:121]
	v_mfma_f32_16x16x32_bf16 v[114:117], v[172:175], v[180:183], v[114:117]
	v_mfma_f32_16x16x32_bf16 v[102:105], v[164:167], v[192:195], v[102:105]
	v_mfma_f32_16x16x32_bf16 v[98:101], v[172:175], v[192:195], v[98:101]
	v_mfma_f32_16x16x32_bf16 v[86:89], v[164:167], v[200:203], v[86:89]
	v_mfma_f32_16x16x32_bf16 v[82:85], v[172:175], v[200:203], v[82:85]
	v_mfma_f32_16x16x32_bf16 v[70:73], v[164:167], v[208:211], v[70:73]
	v_mfma_f32_16x16x32_bf16 v[66:69], v[172:175], v[208:211], v[66:69]
	s_setprio 0
	s_barrier
; #define PG8_STAGE(bufoff, gbase, voff) do { _Pragma("unroll") for (int _i = 0; _i < 2; ++_i) \
;         __builtin_amdgcn_global_load_lds((const unsigned*)((const char*)(gbase) + (voff)[_i]), (LAS unsigned*)(lds + (bufoff) + ldsw + _i * 8192), 16, 0, 0); } while (0)
; #define PG8_LDA(dst, b, h) do { _Pragma("unroll") for (int m = 0; m < 4; ++m) _Pragma("unroll") for (int k = 0; k < 2; ++k) dst[m][k] = *(const LAS bf16x8*)(lds + PG8_SA(b, h) + aoff + m * 2048 + k * 1024); } while (0)
; #define PG8_MMA(ai, bj, At, Bt) do { __builtin_amdgcn_s_setprio(1); _Pragma("unroll") for (int m = 0; m < 4; ++m) _Pragma("unroll") for (int n = 0; n < 2; ++n) _Pragma("unroll") for (int k = 0; k < 2; ++k) \
;         acc[ai][bj][m][n] = __builtin_amdgcn_mfma_f32_16x16x32_bf16(Bt[n][k], At[m][k], acc[ai][bj][m][n], 0, 0, 0); __builtin_amdgcn_s_setprio(0); } while (0)
; #define PG8_WAIT_V(n) asm volatile("s_waitcnt vmcnt(" #n ")" ::: "memory")
; #define PG8_WAIT_L(n) asm volatile("s_waitcnt lgkmcnt(" #n ")" ::: "memory")
; #define PG8_BAR __builtin_amdgcn_s_barrier()
; #define PG8_SCHED __builtin_amdgcn_sched_barrier(0)
; template <class Epi, class Sched>
; __device__ __forceinline__ void gemm_phase(LAS unsigned char* lds, const Gemm g, const Sched& S, const Epi& E) {
;     ...
;             PG8_LDA(At, 1, 1); PG8_STAGE(PG8_SB(1, 0), b3, voffB); PG8_STAGE(PG8_SB(1, 1), b3 + hstep, voffB); PG8_STAGE(PG8_SA(1, 0), a3, voffA);
;             PG8_WAIT_V(8); PG8_WAIT_L(0); PG8_BAR; PG8_MMA(1, 0, At, B0); PG8_MMA(1, 1, At, B1); PG8_BAR; PG8_SCHED;
;         }
	s_add_i32 s1, s1, s4
	s_add_u32 s46, s60, 0x80
	s_addc_u32 s47, s61, 0
	s_mov_b32 m0, s1
	ds_read_b128 v[176:179], v143 offset:49152
	ds_read_b128 v[180:183], v143 offset:50176
	ds_read_b128 v[184:187], v143 offset:51200
	ds_read_b128 v[192:195], v143 offset:52224
	ds_read_b128 v[196:199], v143 offset:53248
	ds_read_b128 v[200:203], v143 offset:54272
	ds_read_b128 v[204:207], v143 offset:55296
	ds_read_b128 v[208:211], v143 offset:56320
	global_load_lds_dwordx4 v0, s[46:47]
	s_add_i32 m0, s1, 0x2000
	s_add_i32 s1, s59, s4
	global_load_lds_dwordx4 v130, s[46:47]
	s_add_u32 s46, s46, s20
	s_addc_u32 s47, s47, s21
	s_mov_b32 m0, s1
	s_nop 0
	global_load_lds_dwordx4 v0, s[46:47]
	s_add_i32 m0, s1, 0x2000
	s_nop 0
	global_load_lds_dwordx4 v130, s[46:47]
	s_add_u32 s46, s50, 0x80
	s_addc_u32 s47, s51, 0
	s_mov_b32 m0, s53
	s_nop 0
	global_load_lds_dwordx4 v134, s[46:47]
	s_mov_b32 m0, s54
	s_nop 0
	global_load_lds_dwordx4 v132, s[46:47]
	s_waitcnt vmcnt(8)
	s_waitcnt lgkmcnt(0)
	s_barrier
	s_setprio 1
	s_waitcnt lgkmcnt(0)
	v_mfma_f32_16x16x32_bf16 v[62:65], v[144:147], v[176:179], v[62:65]
	v_mfma_f32_16x16x32_bf16 v[58:61], v[152:155], v[176:179], v[58:61]
	v_mfma_f32_16x16x32_bf16 v[46:49], v[144:147], v[184:187], v[46:49]
	v_mfma_f32_16x16x32_bf16 v[42:45], v[152:155], v[184:187], v[42:45]
	v_mfma_f32_16x16x32_bf16 v[30:33], v[144:147], v[196:199], v[30:33]
	v_mfma_f32_16x16x32_bf16 v[26:29], v[152:155], v[196:199], v[26:29]
	v_mfma_f32_16x16x32_bf16 v[14:17], v[144:147], v[204:207], v[14:17]
	v_mfma_f32_16x16x32_bf16 v[10:13], v[152:155], v[204:207], v[10:13]
	v_mfma_f32_16x16x32_bf16 v[62:65], v[148:151], v[180:183], v[62:65]
	v_mfma_f32_16x16x32_bf16 v[58:61], v[156:159], v[180:183], v[58:61]
	v_mfma_f32_16x16x32_bf16 v[46:49], v[148:151], v[192:195], v[46:49]
	v_mfma_f32_16x16x32_bf16 v[42:45], v[156:159], v[192:195], v[42:45]
	v_mfma_f32_16x16x32_bf16 v[30:33], v[148:151], v[200:203], v[30:33]
	v_mfma_f32_16x16x32_bf16 v[26:29], v[156:159], v[200:203], v[26:29]
	v_mfma_f32_16x16x32_bf16 v[14:17], v[148:151], v[208:211], v[14:17]
	v_mfma_f32_16x16x32_bf16 v[10:13], v[156:159], v[208:211], v[10:13]
	s_setprio 0
	s_setprio 1
	v_mfma_f32_16x16x32_bf16 v[54:57], v[160:163], v[176:179], v[54:57]
	v_mfma_f32_16x16x32_bf16 v[50:53], v[168:171], v[176:179], v[50:53]
	v_mfma_f32_16x16x32_bf16 v[38:41], v[160:163], v[184:187], v[38:41]
	v_mfma_f32_16x16x32_bf16 v[34:37], v[168:171], v[184:187], v[34:37]
	v_mfma_f32_16x16x32_bf16 v[22:25], v[160:163], v[196:199], v[22:25]
	v_mfma_f32_16x16x32_bf16 v[18:21], v[168:171], v[196:199], v[18:21]
	v_mfma_f32_16x16x32_bf16 v[6:9], v[160:163], v[204:207], v[6:9]
	v_mfma_f32_16x16x32_bf16 v[2:5], v[168:171], v[204:207], v[2:5]
	v_mfma_f32_16x16x32_bf16 v[54:57], v[164:167], v[180:183], v[54:57]
	v_mfma_f32_16x16x32_bf16 v[50:53], v[172:175], v[180:183], v[50:53]
	v_mfma_f32_16x16x32_bf16 v[38:41], v[164:167], v[192:195], v[38:41]
	v_mfma_f32_16x16x32_bf16 v[34:37], v[172:175], v[192:195], v[34:37]
	v_mfma_f32_16x16x32_bf16 v[22:25], v[164:167], v[200:203], v[22:25]
	v_mfma_f32_16x16x32_bf16 v[18:21], v[172:175], v[200:203], v[18:21]
	v_mfma_f32_16x16x32_bf16 v[6:9], v[164:167], v[208:211], v[6:9]
	v_mfma_f32_16x16x32_bf16 v[2:5], v[172:175], v[208:211], v[2:5]
	s_setprio 0
	s_barrier
	s_cmp_ge_i32 s58, s55
	s_mov_b64 s[46:47], s[48:49]
	s_mov_b32 s50, s58
	s_cbranch_scc0 .LBB0_131

; #define PG8_STAGE(bufoff, gbase, voff) do { _Pragma("unroll") for (int _i = 0; _i < 2; ++_i) \
;         __builtin_amdgcn_global_load_lds((const unsigned*)((const char*)(gbase) + (voff)[_i]), (LAS unsigned*)(lds + (bufoff) + ldsw + _i * 8192), 16, 0, 0); } while (0)
; #define PG8_LDA(dst, b, h) do { _Pragma("unroll") for (int m = 0; m < 4; ++m) _Pragma("unroll") for (int k = 0; k < 2; ++k) dst[m][k] = *(const LAS bf16x8*)(lds + PG8_SA(b, h) + aoff + m * 2048 + k * 1024); } while (0)
; #define PG8_LDB(dst, b, h) do { _Pragma("unroll") for (int n = 0; n < 2; ++n) _Pragma("unroll") for (int k = 0; k < 2; ++k) dst[n][k] = *(const LAS bf16x8*)(lds + PG8_SB(b, h) + boff + n * 2048 + k * 1024); } while (0)
; #define PG8_MMA(ai, bj, At, Bt) do { __builtin_amdgcn_s_setprio(1); _Pragma("unroll") for (int m = 0; m < 4; ++m) _Pragma("unroll") for (int n = 0; n < 2; ++n) _Pragma("unroll") for (int k = 0; k < 2; ++k) \
;         acc[ai][bj][m][n] = __builtin_amdgcn_mfma_f32_16x16x32_bf16(Bt[n][k], At[m][k], acc[ai][bj][m][n], 0, 0, 0); __builtin_amdgcn_s_setprio(0); } while (0)
; #define PG8_WAIT_V(n) asm volatile("s_waitcnt vmcnt(" #n ")" ::: "memory")
; #define PG8_WAIT_L(n) asm volatile("s_waitcnt lgkmcnt(" #n ")" ::: "memory")
; #define PG8_BAR __builtin_amdgcn_s_barrier()
; #define PG8_SCHED __builtin_amdgcn_sched_barrier(0)
; template <class Epi, class Sched>
; __device__ __forceinline__ void gemm_phase(LAS unsigned char* lds, const Gemm g, const Sched& S, const Epi& E) {
;     ...
;         for (int t = 0; t < nt; t += 2) {
;             const bool last = (t == nt - 2);
;             const char* a1 = cA + (size_t)(t + 1) * kstep;
;             const char* a2 = last ? nA : cA + (size_t)(t + 2) * kstep; const char* b2 = last ? nB : cB + (size_t)(t + 2) * kstep;
;             const char* a3 = a2 + kstep; const char* b3 = b2 + kstep;
;             if (last && has_next) S.a_ready(nxt);
;             PG8_LDB(B0, 0, 0); PG8_LDB(B1, 0, 1); PG8_SCHED; PG8_LDA(At, 0, 0); PG8_STAGE(PG8_SA(1, 1), a1 + hstep, voffA);
;             PG8_WAIT_V(8); PG8_WAIT_L(0); PG8_BAR; PG8_MMA(0, 0, At, B0); PG8_MMA(0, 1, At, B1); PG8_BAR; PG8_SCHED;
;             PG8_LDA(At, 0, 1); PG8_STAGE(PG8_SB(0, 0), b2, voffB); PG8_STAGE(PG8_SB(0, 1), b2 + hstep, voffB); PG8_STAGE(PG8_SA(0, 0), a2, voffA);
.LBB0_435:
	s_cmp_eq_u32 s52, 0
	s_cselect_b32 s99, 1, 0
	s_cmp_eq_u32 s8, 0
	s_cselect_b32 s99, 0, s99
	s_add_i32 s62, s52, 2
	s_add_u32 s50, s48, 0x100
	s_addc_u32 s51, s49, 0
	s_add_u32 s1, s9, s48
	s_addc_u32 s53, s36, s49
	s_cmp_eq_u32 s60, s52
	s_cselect_b32 s52, s100, s50
	s_cselect_b32 s63, 0, s51
	s_cselect_b32 s64, s46, s1
	s_cselect_b32 s65, s47, s53
	s_add_u32 s52, s2, s52
	s_addc_u32 s53, s3, s63
	s_add_i32 s1, 0, 0x10000
	s_add_i32 s63, 0, 0x14000
	v_add_u32_e32 v156, s1, v142
	v_add_u32_e32 v172, s63, v142
	ds_read_b128 v[144:147], v156
	ds_read_b128 v[148:151], v156 offset:1024
	ds_read_b128 v[152:155], v156 offset:2048
	ds_read_b128 v[156:159], v156 offset:3072
	ds_read_b128 v[160:163], v172
	ds_read_b128 v[164:167], v172 offset:1024
	ds_read_b128 v[168:171], v172 offset:2048
	ds_read_b128 v[172:175], v172 offset:3072
	s_add_u32 s48, s48, s2
	s_addc_u32 s49, s49, s3
	s_add_u32 s48, s48, s26
	s_addc_u32 s49, s49, s27
	s_add_u32 s48, s48, 0x80
	s_addc_u32 s49, s49, 0
	s_add_i32 m0, s5, 0xc000
	ds_read_b128 v[176:179], v143
	ds_read_b128 v[180:183], v143 offset:1024
	ds_read_b128 v[184:187], v143 offset:2048
	ds_read_b128 v[192:195], v143 offset:3072
	ds_read_b128 v[196:199], v143 offset:4096
	ds_read_b128 v[200:203], v143 offset:5120
	ds_read_b128 v[204:207], v143 offset:6144
	ds_read_b128 v[208:211], v143 offset:7168
	global_load_lds_dwordx4 v134, s[48:49]
	s_add_i32 m0, s5, 0xe000
	s_nop 0
	global_load_lds_dwordx4 v132, s[48:49]
	s_cmp_eq_u32 s99, 1
	s_cbranch_scc1 .Lfw_mlp1_0_first
	s_waitcnt vmcnt(8)
	s_branch .Lfw_mlp1_0_join

; #define PG8_STAGE(bufoff, gbase, voff) do { _Pragma("unroll") for (int _i = 0; _i < 2; ++_i) \
;         __builtin_amdgcn_global_load_lds((const unsigned*)((const char*)(gbase) + (voff)[_i]), (LAS unsigned*)(lds + (bufoff) + ldsw + _i * 8192), 16, 0, 0); } while (0)
; #define PG8_LDA(dst, b, h) do { _Pragma("unroll") for (int m = 0; m < 4; ++m) _Pragma("unroll") for (int k = 0; k < 2; ++k) dst[m][k] = *(const LAS bf16x8*)(lds + PG8_SA(b, h) + aoff + m * 2048 + k * 1024); } while (0)
; #define PG8_MMA(ai, bj, At, Bt) do { __builtin_amdgcn_s_setprio(1); _Pragma("unroll") for (int m = 0; m < 4; ++m) _Pragma("unroll") for (int n = 0; n < 2; ++n) _Pragma("unroll") for (int k = 0; k < 2; ++k) \
;         acc[ai][bj][m][n] = __builtin_amdgcn_mfma_f32_16x16x32_bf16(Bt[n][k], At[m][k], acc[ai][bj][m][n], 0, 0, 0); __builtin_amdgcn_s_setprio(0); } while (0)
; #define PG8_WAIT_V(n) asm volatile("s_waitcnt vmcnt(" #n ")" ::: "memory")
; #define PG8_WAIT_L(n) asm volatile("s_waitcnt lgkmcnt(" #n ")" ::: "memory")
; #define PG8_BAR __builtin_amdgcn_s_barrier()
; #define PG8_SCHED __builtin_amdgcn_sched_barrier(0)
; template <class Epi, class Sched>
; __device__ __forceinline__ void gemm_phase(LAS unsigned char* lds, const Gemm g, const Sched& S, const Epi& E) {
;     ...
;             PG8_WAIT_V(8); PG8_WAIT_L(0); PG8_BAR; PG8_MMA(0, 0, At, B0); PG8_MMA(0, 1, At, B1); PG8_BAR; PG8_SCHED;
;             PG8_LDA(At, 0, 1); PG8_STAGE(PG8_SB(0, 0), b2, voffB); PG8_STAGE(PG8_SB(0, 1), b2 + hstep, voffB); PG8_STAGE(PG8_SA(0, 0), a2, voffA);
;             PG8_WAIT_V(8); PG8_WAIT_L(0); PG8_BAR; PG8_MMA(1, 0, At, B0); PG8_MMA(1, 1, At, B1); PG8_BAR; PG8_SCHED;
.Lfw_mlp1_0_join:
	s_waitcnt lgkmcnt(0)
	s_barrier
	s_setprio 1
	s_waitcnt lgkmcnt(0)
	v_mfma_f32_16x16x32_bf16 v[122:125], v[144:147], v[176:179], v[122:125]
	v_mfma_f32_16x16x32_bf16 v[126:129], v[152:155], v[176:179], v[126:129]
	v_mfma_f32_16x16x32_bf16 v[110:113], v[144:147], v[184:187], v[110:113]
	v_mfma_f32_16x16x32_bf16 v[106:109], v[152:155], v[184:187], v[106:109]
	v_mfma_f32_16x16x32_bf16 v[94:97], v[144:147], v[196:199], v[94:97]
	v_mfma_f32_16x16x32_bf16 v[90:93], v[152:155], v[196:199], v[90:93]
	v_mfma_f32_16x16x32_bf16 v[78:81], v[144:147], v[204:207], v[78:81]
	v_mfma_f32_16x16x32_bf16 v[74:77], v[152:155], v[204:207], v[74:77]
	v_mfma_f32_16x16x32_bf16 v[122:125], v[148:151], v[180:183], v[122:125]
	v_mfma_f32_16x16x32_bf16 v[126:129], v[156:159], v[180:183], v[126:129]
	v_mfma_f32_16x16x32_bf16 v[110:113], v[148:151], v[192:195], v[110:113]
	v_mfma_f32_16x16x32_bf16 v[106:109], v[156:159], v[192:195], v[106:109]
	v_mfma_f32_16x16x32_bf16 v[94:97], v[148:151], v[200:203], v[94:97]
	v_mfma_f32_16x16x32_bf16 v[90:93], v[156:159], v[200:203], v[90:93]
	v_mfma_f32_16x16x32_bf16 v[78:81], v[148:151], v[208:211], v[78:81]
	v_mfma_f32_16x16x32_bf16 v[74:77], v[156:159], v[208:211], v[74:77]
	s_setprio 0
	s_setprio 1
	v_mfma_f32_16x16x32_bf16 v[118:121], v[160:163], v[176:179], v[118:121]
	v_mfma_f32_16x16x32_bf16 v[114:117], v[168:171], v[176:179], v[114:117]
	v_mfma_f32_16x16x32_bf16 v[102:105], v[160:163], v[184:187], v[102:105]
	v_mfma_f32_16x16x32_bf16 v[98:101], v[168:171], v[184:187], v[98:101]
	v_mfma_f32_16x16x32_bf16 v[86:89], v[160:163], v[196:199], v[86:89]
	v_mfma_f32_16x16x32_bf16 v[82:85], v[168:171], v[196:199], v[82:85]
	v_mfma_f32_16x16x32_bf16 v[70:73], v[160:163], v[204:207], v[70:73]
	v_mfma_f32_16x16x32_bf16 v[66:69], v[168:171], v[204:207], v[66:69]
	v_mfma_f32_16x16x32_bf16 v[118:121], v[164:167], v[180:183], v[118:121]
	v_mfma_f32_16x16x32_bf16 v[114:117], v[172:175], v[180:183], v[114:117]
	v_mfma_f32_16x16x32_bf16 v[102:105], v[164:167], v[192:195], v[102:105]
	v_mfma_f32_16x16x32_bf16 v[98:101], v[172:175], v[192:195], v[98:101]
	v_mfma_f32_16x16x32_bf16 v[86:89], v[164:167], v[200:203], v[86:89]
	v_mfma_f32_16x16x32_bf16 v[82:85], v[172:175], v[200:203], v[82:85]
	v_mfma_f32_16x16x32_bf16 v[70:73], v[164:167], v[208:211], v[70:73]
	v_mfma_f32_16x16x32_bf16 v[66:69], v[172:175], v[208:211], v[66:69]
	s_setprio 0
	s_barrier
	s_add_i32 s1, s1, s4
	s_mov_b32 m0, s1
	ds_read_b128 v[176:179], v143 offset:16384
	ds_read_b128 v[180:183], v143 offset:17408
	ds_read_b128 v[184:187], v143 offset:18432
	ds_read_b128 v[192:195], v143 offset:19456
	ds_read_b128 v[196:199], v143 offset:20480
	ds_read_b128 v[200:203], v143 offset:21504
	ds_read_b128 v[204:207], v143 offset:22528
	ds_read_b128 v[208:211], v143 offset:23552
	global_load_lds_dwordx4 v0, s[64:65]
	s_add_i32 m0, s1, 0x2000
	s_add_u32 s48, s64, s26
	s_addc_u32 s49, s65, s27
	s_add_i32 s1, s63, s4
	global_load_lds_dwordx4 v130, s[64:65]
	s_mov_b32 m0, s1
	s_nop 0
	global_load_lds_dwordx4 v0, s[48:49]
	s_add_i32 m0, s1, 0x2000
	s_nop 0
	global_load_lds_dwordx4 v130, s[48:49]
	s_mov_b32 m0, s5
	s_nop 0
	global_load_lds_dwordx4 v134, s[52:53]
	s_mov_b32 m0, s54
	s_nop 0
	global_load_lds_dwordx4 v132, s[52:53]
	s_cmp_eq_u32 s99, 1
	s_cbranch_scc1 .Lfw_mlp1_1_first
	s_waitcnt vmcnt(8)
	s_branch .Lfw_mlp1_1_join

; #define PG8_STAGE(bufoff, gbase, voff) do { _Pragma("unroll") for (int _i = 0; _i < 2; ++_i) \
;         __builtin_amdgcn_global_load_lds((const unsigned*)((const char*)(gbase) + (voff)[_i]), (LAS unsigned*)(lds + (bufoff) + ldsw + _i * 8192), 16, 0, 0); } while (0)
; #define PG8_LDA(dst, b, h) do { _Pragma("unroll") for (int m = 0; m < 4; ++m) _Pragma("unroll") for (int k = 0; k < 2; ++k) dst[m][k] = *(const LAS bf16x8*)(lds + PG8_SA(b, h) + aoff + m * 2048 + k * 1024); } while (0)
; #define PG8_LDB(dst, b, h) do { _Pragma("unroll") for (int n = 0; n < 2; ++n) _Pragma("unroll") for (int k = 0; k < 2; ++k) dst[n][k] = *(const LAS bf16x8*)(lds + PG8_SB(b, h) + boff + n * 2048 + k * 1024); } while (0)
; #define PG8_MMA(ai, bj, At, Bt) do { __builtin_amdgcn_s_setprio(1); _Pragma("unroll") for (int m = 0; m < 4; ++m) _Pragma("unroll") for (int n = 0; n < 2; ++n) _Pragma("unroll") for (int k = 0; k < 2; ++k) \
;         acc[ai][bj][m][n] = __builtin_amdgcn_mfma_f32_16x16x32_bf16(Bt[n][k], At[m][k], acc[ai][bj][m][n], 0, 0, 0); __builtin_amdgcn_s_setprio(0); } while (0)
; #define PG8_WAIT_V(n) asm volatile("s_waitcnt vmcnt(" #n ")" ::: "memory")
; #define PG8_WAIT_L(n) asm volatile("s_waitcnt lgkmcnt(" #n ")" ::: "memory")
; #define PG8_BAR __builtin_amdgcn_s_barrier()
; #define PG8_SCHED __builtin_amdgcn_sched_barrier(0)
; template <class Epi, class Sched>
; __device__ __forceinline__ void gemm_phase(LAS unsigned char* lds, const Gemm g, const Sched& S, const Epi& E) {
;     ...
;             PG8_WAIT_V(8); PG8_WAIT_L(0); PG8_BAR; PG8_MMA(1, 0, At, B0); PG8_MMA(1, 1, At, B1); PG8_BAR; PG8_SCHED;
;             PG8_LDB(B0, 1, 0); PG8_LDB(B1, 1, 1); PG8_SCHED; PG8_LDA(At, 1, 0); PG8_STAGE(PG8_SA(0, 1), a2 + hstep, voffA);
;             PG8_WAIT_V(8); PG8_WAIT_L(0); PG8_BAR; PG8_MMA(0, 0, At, B0); PG8_MMA(0, 1, At, B1); PG8_BAR; PG8_SCHED;
;             PG8_LDA(At, 1, 1); PG8_STAGE(PG8_SB(1, 0), b3, voffB); PG8_STAGE(PG8_SB(1, 1), b3 + hstep, voffB); PG8_STAGE(PG8_SA(1, 0), a3, voffA);
.Lfw_mlp1_1_join:
	s_waitcnt lgkmcnt(0)
	s_barrier
	s_setprio 1
	s_waitcnt lgkmcnt(0)
	v_mfma_f32_16x16x32_bf16 v[62:65], v[144:147], v[176:179], v[62:65]
	v_mfma_f32_16x16x32_bf16 v[58:61], v[152:155], v[176:179], v[58:61]
	v_mfma_f32_16x16x32_bf16 v[46:49], v[144:147], v[184:187], v[46:49]
	v_mfma_f32_16x16x32_bf16 v[42:45], v[152:155], v[184:187], v[42:45]
	v_mfma_f32_16x16x32_bf16 v[30:33], v[144:147], v[196:199], v[30:33]
	v_mfma_f32_16x16x32_bf16 v[26:29], v[152:155], v[196:199], v[26:29]
	v_mfma_f32_16x16x32_bf16 v[14:17], v[144:147], v[204:207], v[14:17]
	v_mfma_f32_16x16x32_bf16 v[10:13], v[152:155], v[204:207], v[10:13]
	v_mfma_f32_16x16x32_bf16 v[62:65], v[148:151], v[180:183], v[62:65]
	v_mfma_f32_16x16x32_bf16 v[58:61], v[156:159], v[180:183], v[58:61]
	v_mfma_f32_16x16x32_bf16 v[46:49], v[148:151], v[192:195], v[46:49]
	v_mfma_f32_16x16x32_bf16 v[42:45], v[156:159], v[192:195], v[42:45]
	v_mfma_f32_16x16x32_bf16 v[30:33], v[148:151], v[200:203], v[30:33]
	v_mfma_f32_16x16x32_bf16 v[26:29], v[156:159], v[200:203], v[26:29]
	v_mfma_f32_16x16x32_bf16 v[14:17], v[148:151], v[208:211], v[14:17]
	v_mfma_f32_16x16x32_bf16 v[10:13], v[156:159], v[208:211], v[10:13]
	s_setprio 0
	s_setprio 1
	v_mfma_f32_16x16x32_bf16 v[54:57], v[160:163], v[176:179], v[54:57]
	v_mfma_f32_16x16x32_bf16 v[50:53], v[168:171], v[176:179], v[50:53]
	v_mfma_f32_16x16x32_bf16 v[38:41], v[160:163], v[184:187], v[38:41]
	v_mfma_f32_16x16x32_bf16 v[34:37], v[168:171], v[184:187], v[34:37]
	v_mfma_f32_16x16x32_bf16 v[22:25], v[160:163], v[196:199], v[22:25]
	v_mfma_f32_16x16x32_bf16 v[18:21], v[168:171], v[196:199], v[18:21]
	v_mfma_f32_16x16x32_bf16 v[6:9], v[160:163], v[204:207], v[6:9]
	v_mfma_f32_16x16x32_bf16 v[2:5], v[168:171], v[204:207], v[2:5]
	v_mfma_f32_16x16x32_bf16 v[54:57], v[164:167], v[180:183], v[54:57]
	v_mfma_f32_16x16x32_bf16 v[50:53], v[172:175], v[180:183], v[50:53]
	v_mfma_f32_16x16x32_bf16 v[38:41], v[164:167], v[192:195], v[38:41]
	v_mfma_f32_16x16x32_bf16 v[34:37], v[172:175], v[192:195], v[34:37]
	v_mfma_f32_16x16x32_bf16 v[22:25], v[164:167], v[200:203], v[22:25]
	v_mfma_f32_16x16x32_bf16 v[18:21], v[172:175], v[200:203], v[18:21]
	v_mfma_f32_16x16x32_bf16 v[6:9], v[164:167], v[208:211], v[6:9]
	v_mfma_f32_16x16x32_bf16 v[2:5], v[172:175], v[208:211], v[2:5]
	s_setprio 0
	s_barrier
	s_add_i32 s1, 0, 0x18000
	s_add_i32 s63, 0, 0x1c000
	v_add_u32_e32 v156, s1, v142
	v_add_u32_e32 v172, s63, v142
	ds_read_b128 v[144:147], v156
	ds_read_b128 v[148:151], v156 offset:1024
	ds_read_b128 v[152:155], v156 offset:2048
	ds_read_b128 v[156:159], v156 offset:3072
	ds_read_b128 v[160:163], v172
	ds_read_b128 v[164:167], v172 offset:1024
	ds_read_b128 v[168:171], v172 offset:2048
	ds_read_b128 v[172:175], v172 offset:3072
	s_add_u32 s48, s52, s26
	s_addc_u32 s49, s53, s27
	s_mov_b32 m0, s55
	ds_read_b128 v[176:179], v143 offset:32768
	ds_read_b128 v[180:183], v143 offset:33792
	ds_read_b128 v[184:187], v143 offset:34816
	ds_read_b128 v[192:195], v143 offset:35840
	ds_read_b128 v[196:199], v143 offset:36864
	ds_read_b128 v[200:203], v143 offset:37888
	ds_read_b128 v[204:207], v143 offset:38912
	ds_read_b128 v[208:211], v143 offset:39936
	global_load_lds_dwordx4 v134, s[48:49]
	s_mov_b32 m0, s56
	s_nop 0
	global_load_lds_dwordx4 v132, s[48:49]
	s_waitcnt vmcnt(8)
	s_waitcnt lgkmcnt(0)
	s_barrier
	s_setprio 1
	s_waitcnt lgkmcnt(0)
	v_mfma_f32_16x16x32_bf16 v[122:125], v[144:147], v[176:179], v[122:125]
	v_mfma_f32_16x16x32_bf16 v[126:129], v[152:155], v[176:179], v[126:129]
	v_mfma_f32_16x16x32_bf16 v[110:113], v[144:147], v[184:187], v[110:113]
	v_mfma_f32_16x16x32_bf16 v[106:109], v[152:155], v[184:187], v[106:109]
	v_mfma_f32_16x16x32_bf16 v[94:97], v[144:147], v[196:199], v[94:97]
	v_mfma_f32_16x16x32_bf16 v[90:93], v[152:155], v[196:199], v[90:93]
	v_mfma_f32_16x16x32_bf16 v[78:81], v[144:147], v[204:207], v[78:81]
	v_mfma_f32_16x16x32_bf16 v[74:77], v[152:155], v[204:207], v[74:77]
	v_mfma_f32_16x16x32_bf16 v[122:125], v[148:151], v[180:183], v[122:125]
	v_mfma_f32_16x16x32_bf16 v[126:129], v[156:159], v[180:183], v[126:129]
	v_mfma_f32_16x16x32_bf16 v[110:113], v[148:151], v[192:195], v[110:113]
	v_mfma_f32_16x16x32_bf16 v[106:109], v[156:159], v[192:195], v[106:109]
	v_mfma_f32_16x16x32_bf16 v[94:97], v[148:151], v[200:203], v[94:97]
	v_mfma_f32_16x16x32_bf16 v[90:93], v[156:159], v[200:203], v[90:93]
	v_mfma_f32_16x16x32_bf16 v[78:81], v[148:151], v[208:211], v[78:81]
	v_mfma_f32_16x16x32_bf16 v[74:77], v[156:159], v[208:211], v[74:77]
	s_setprio 0
	s_setprio 1
	v_mfma_f32_16x16x32_bf16 v[118:121], v[160:163], v[176:179], v[118:121]
	v_mfma_f32_16x16x32_bf16 v[114:117], v[168:171], v[176:179], v[114:117]
	v_mfma_f32_16x16x32_bf16 v[102:105], v[160:163], v[184:187], v[102:105]
	v_mfma_f32_16x16x32_bf16 v[98:101], v[168:171], v[184:187], v[98:101]
	v_mfma_f32_16x16x32_bf16 v[86:89], v[160:163], v[196:199], v[86:89]
	v_mfma_f32_16x16x32_bf16 v[82:85], v[168:171], v[196:199], v[82:85]
	v_mfma_f32_16x16x32_bf16 v[70:73], v[160:163], v[204:207], v[70:73]
	v_mfma_f32_16x16x32_bf16 v[66:69], v[168:171], v[204:207], v[66:69]
	v_mfma_f32_16x16x32_bf16 v[118:121], v[164:167], v[180:183], v[118:121]
	v_mfma_f32_16x16x32_bf16 v[114:117], v[172:175], v[180:183], v[114:117]
	v_mfma_f32_16x16x32_bf16 v[102:105], v[164:167], v[192:195], v[102:105]
	v_mfma_f32_16x16x32_bf16 v[98:101], v[172:175], v[192:195], v[98:101]
	v_mfma_f32_16x16x32_bf16 v[86:89], v[164:167], v[200:203], v[86:89]
	v_mfma_f32_16x16x32_bf16 v[82:85], v[172:175], v[200:203], v[82:85]
	v_mfma_f32_16x16x32_bf16 v[70:73], v[164:167], v[208:211], v[70:73]
	v_mfma_f32_16x16x32_bf16 v[66:69], v[172:175], v[208:211], v[66:69]
	s_setprio 0
	s_barrier
; #define PG8_STAGE(bufoff, gbase, voff) do { _Pragma("unroll") for (int _i = 0; _i < 2; ++_i) \
;         __builtin_amdgcn_global_load_lds((const unsigned*)((const char*)(gbase) + (voff)[_i]), (LAS unsigned*)(lds + (bufoff) + ldsw + _i * 8192), 16, 0, 0); } while (0)
; #define PG8_LDA(dst, b, h) do { _Pragma("unroll") for (int m = 0; m < 4; ++m) _Pragma("unroll") for (int k = 0; k < 2; ++k) dst[m][k] = *(const LAS bf16x8*)(lds + PG8_SA(b, h) + aoff + m * 2048 + k * 1024); } while (0)
; #define PG8_MMA(ai, bj, At, Bt) do { __builtin_amdgcn_s_setprio(1); _Pragma("unroll") for (int m = 0; m < 4; ++m) _Pragma("unroll") for (int n = 0; n < 2; ++n) _Pragma("unroll") for (int k = 0; k < 2; ++k) \
;         acc[ai][bj][m][n] = __builtin_amdgcn_mfma_f32_16x16x32_bf16(Bt[n][k], At[m][k], acc[ai][bj][m][n], 0, 0, 0); __builtin_amdgcn_s_setprio(0); } while (0)
; #define PG8_WAIT_V(n) asm volatile("s_waitcnt vmcnt(" #n ")" ::: "memory")
; #define PG8_WAIT_L(n) asm volatile("s_waitcnt lgkmcnt(" #n ")" ::: "memory")
; #define PG8_BAR __builtin_amdgcn_s_barrier()
; #define PG8_SCHED __builtin_amdgcn_sched_barrier(0)
; template <class Epi, class Sched>
; __device__ __forceinline__ void gemm_phase(LAS unsigned char* lds, const Gemm g, const Sched& S, const Epi& E) {
;     ...
;             PG8_LDA(At, 1, 1); PG8_STAGE(PG8_SB(1, 0), b3, voffB); PG8_STAGE(PG8_SB(1, 1), b3 + hstep, voffB); PG8_STAGE(PG8_SA(1, 0), a3, voffA);
;             PG8_WAIT_V(8); PG8_WAIT_L(0); PG8_BAR; PG8_MMA(1, 0, At, B0); PG8_MMA(1, 1, At, B1); PG8_BAR; PG8_SCHED;
;         }
	s_add_i32 s1, s1, s4
	s_add_u32 s48, s64, 0x80
	s_addc_u32 s49, s65, 0
	s_mov_b32 m0, s1
	ds_read_b128 v[176:179], v143 offset:49152
	ds_read_b128 v[180:183], v143 offset:50176
	ds_read_b128 v[184:187], v143 offset:51200
	ds_read_b128 v[192:195], v143 offset:52224
	ds_read_b128 v[196:199], v143 offset:53248
	ds_read_b128 v[200:203], v143 offset:54272
	ds_read_b128 v[204:207], v143 offset:55296
	ds_read_b128 v[208:211], v143 offset:56320
	global_load_lds_dwordx4 v0, s[48:49]
	s_add_i32 m0, s1, 0x2000
	s_add_i32 s1, s63, s4
	global_load_lds_dwordx4 v130, s[48:49]
	s_add_u32 s48, s48, s26
	s_addc_u32 s49, s49, s27
	s_mov_b32 m0, s1
	s_nop 0
	global_load_lds_dwordx4 v0, s[48:49]
	s_add_i32 m0, s1, 0x2000
	s_nop 0
	global_load_lds_dwordx4 v130, s[48:49]
	s_add_u32 s48, s52, 0x80
	s_addc_u32 s49, s53, 0
	s_mov_b32 m0, s57
	s_nop 0
	global_load_lds_dwordx4 v134, s[48:49]
	s_mov_b32 m0, s58
	s_nop 0
	global_load_lds_dwordx4 v132, s[48:49]
	s_waitcnt vmcnt(8)
	s_waitcnt lgkmcnt(0)
	s_barrier
	s_setprio 1
	s_waitcnt lgkmcnt(0)
	v_mfma_f32_16x16x32_bf16 v[62:65], v[144:147], v[176:179], v[62:65]
	v_mfma_f32_16x16x32_bf16 v[58:61], v[152:155], v[176:179], v[58:61]
	v_mfma_f32_16x16x32_bf16 v[46:49], v[144:147], v[184:187], v[46:49]
	v_mfma_f32_16x16x32_bf16 v[42:45], v[152:155], v[184:187], v[42:45]
	v_mfma_f32_16x16x32_bf16 v[30:33], v[144:147], v[196:199], v[30:33]
	v_mfma_f32_16x16x32_bf16 v[26:29], v[152:155], v[196:199], v[26:29]
	v_mfma_f32_16x16x32_bf16 v[14:17], v[144:147], v[204:207], v[14:17]
	v_mfma_f32_16x16x32_bf16 v[10:13], v[152:155], v[204:207], v[10:13]
	v_mfma_f32_16x16x32_bf16 v[62:65], v[148:151], v[180:183], v[62:65]
	v_mfma_f32_16x16x32_bf16 v[58:61], v[156:159], v[180:183], v[58:61]
	v_mfma_f32_16x16x32_bf16 v[46:49], v[148:151], v[192:195], v[46:49]
	v_mfma_f32_16x16x32_bf16 v[42:45], v[156:159], v[192:195], v[42:45]
	v_mfma_f32_16x16x32_bf16 v[30:33], v[148:151], v[200:203], v[30:33]
	v_mfma_f32_16x16x32_bf16 v[26:29], v[156:159], v[200:203], v[26:29]
	v_mfma_f32_16x16x32_bf16 v[14:17], v[148:151], v[208:211], v[14:17]
	v_mfma_f32_16x16x32_bf16 v[10:13], v[156:159], v[208:211], v[10:13]
	s_setprio 0
	s_setprio 1
	v_mfma_f32_16x16x32_bf16 v[54:57], v[160:163], v[176:179], v[54:57]
	v_mfma_f32_16x16x32_bf16 v[50:53], v[168:171], v[176:179], v[50:53]
	v_mfma_f32_16x16x32_bf16 v[38:41], v[160:163], v[184:187], v[38:41]
	v_mfma_f32_16x16x32_bf16 v[34:37], v[168:171], v[184:187], v[34:37]
	v_mfma_f32_16x16x32_bf16 v[22:25], v[160:163], v[196:199], v[22:25]
	v_mfma_f32_16x16x32_bf16 v[18:21], v[168:171], v[196:199], v[18:21]
	v_mfma_f32_16x16x32_bf16 v[6:9], v[160:163], v[204:207], v[6:9]
	v_mfma_f32_16x16x32_bf16 v[2:5], v[168:171], v[204:207], v[2:5]
	v_mfma_f32_16x16x32_bf16 v[54:57], v[164:167], v[180:183], v[54:57]
	v_mfma_f32_16x16x32_bf16 v[50:53], v[172:175], v[180:183], v[50:53]
	v_mfma_f32_16x16x32_bf16 v[38:41], v[164:167], v[192:195], v[38:41]
	v_mfma_f32_16x16x32_bf16 v[34:37], v[172:175], v[192:195], v[34:37]
	v_mfma_f32_16x16x32_bf16 v[22:25], v[164:167], v[200:203], v[22:25]
	v_mfma_f32_16x16x32_bf16 v[18:21], v[172:175], v[200:203], v[18:21]
	v_mfma_f32_16x16x32_bf16 v[6:9], v[164:167], v[208:211], v[6:9]
	v_mfma_f32_16x16x32_bf16 v[2:5], v[172:175], v[208:211], v[2:5]
	s_setprio 0
	s_barrier
	s_cmp_ge_i32 s62, s59
	s_mov_b64 s[48:49], s[50:51]
	s_mov_b32 s52, s62
	s_cbranch_scc0 .LBB0_435
